# dilated epilogue: eight 8-byte stores per lane paired into four 16-byte stores via permlane32_swap
# speedup vs baseline: 1.0107x; 1.0107x over previous
.LBB0_472:
	v_mov_b32_e32 v0, v139
	s_nop 1
	v_permlane32_swap_b32_e32 v139, v0
	v_add_f32_e32 v0, v139, v0
	v_div_scale_f32 v34, s[52:53], v0, v0, 1.0
	v_rcp_f32_e32 v35, v34
	s_lshl_b32 s10, s58, 15
	v_mov_b32_e32 v133, v1
	v_fma_f32 v36, -v34, v35, 1.0
	v_fmac_f32_e32 v35, v36, v35
	v_div_scale_f32 v36, vcc, 1.0, v0, 1.0
	v_mul_f32_e32 v37, v36, v35
	v_fma_f32 v38, -v34, v37, v36
	v_fmac_f32_e32 v37, v38, v35
	v_fma_f32 v34, -v34, v37, v36
	v_div_fmas_f32 v34, v34, v35, v37
	v_div_fixup_f32 v36, v34, v0, 1.0
	v_lshl_add_u64 v[34:35], v[130:131], 0, s[10:11]
	v_lshlrev_b64 v[38:39], 10, v[34:35]
	v_lshl_add_u64 v[38:39], s[42:43], 0, v[38:39]
	v_lshl_add_u64 v[40:41], v[132:133], 2, v[38:39]
	v_pk_mul_f32 v[18:19], v[18:19], v[36:37] op_sel_hi:[1,0]
	v_pk_mul_f32 v[20:21], v[20:21], v[36:37] op_sel_hi:[1,0]
	v_pk_mul_f32 v[22:23], v[22:23], v[36:37] op_sel_hi:[1,0]
	v_pk_mul_f32 v[24:25], v[24:25], v[36:37] op_sel_hi:[1,0]
	v_pk_mul_f32 v[26:27], v[26:27], v[36:37] op_sel_hi:[1,0]
	v_pk_mul_f32 v[28:29], v[28:29], v[36:37] op_sel_hi:[1,0]
	v_pk_mul_f32 v[30:31], v[30:31], v[36:37] op_sel_hi:[1,0]
	v_pk_mul_f32 v[32:33], v[32:33], v[36:37] op_sel_hi:[1,0]
	v_pk_mul_f32 v[2:3], v[2:3], v[36:37] op_sel_hi:[1,0]
	v_pk_mul_f32 v[4:5], v[4:5], v[36:37] op_sel_hi:[1,0]
	v_pk_mul_f32 v[6:7], v[6:7], v[36:37] op_sel_hi:[1,0]
	v_pk_mul_f32 v[8:9], v[8:9], v[36:37] op_sel_hi:[1,0]
	v_pk_mul_f32 v[10:11], v[10:11], v[36:37] op_sel_hi:[1,0]
	v_pk_mul_f32 v[12:13], v[12:13], v[36:37] op_sel_hi:[1,0]
	v_pk_mul_f32 v[14:15], v[14:15], v[36:37] op_sel_hi:[1,0]
	v_pk_mul_f32 v[16:17], v[16:17], v[36:37] op_sel_hi:[1,0]
	v_cvt_pk_bf16_f32 v18, v18, v19
	v_cvt_pk_bf16_f32 v19, v20, v21
	v_cvt_pk_bf16_f32 v20, v22, v23
	v_cvt_pk_bf16_f32 v21, v24, v25
	v_cvt_pk_bf16_f32 v26, v26, v27
	v_cvt_pk_bf16_f32 v27, v28, v29
	v_cvt_pk_bf16_f32 v28, v30, v31
	v_cvt_pk_bf16_f32 v29, v32, v33
	v_cvt_pk_bf16_f32 v2, v2, v3
	v_cvt_pk_bf16_f32 v3, v4, v5
	v_cvt_pk_bf16_f32 v4, v6, v7
	v_cvt_pk_bf16_f32 v5, v8, v9
	v_cvt_pk_bf16_f32 v10, v10, v11
	v_cvt_pk_bf16_f32 v11, v12, v13
	v_cvt_pk_bf16_f32 v12, v14, v15
	v_cvt_pk_bf16_f32 v13, v16, v17
	v_cmp_gt_u32_e32 vcc, 32, v153
	v_permlane32_swap_b32_e32 v18, v20
	v_permlane32_swap_b32_e32 v19, v21
	v_permlane32_swap_b32_e32 v26, v28
	v_permlane32_swap_b32_e32 v27, v29
	v_permlane32_swap_b32_e32 v2, v4
	v_permlane32_swap_b32_e32 v3, v5
	v_permlane32_swap_b32_e32 v10, v12
	v_permlane32_swap_b32_e32 v11, v13
	global_store_dwordx4 v[40:41], v[18:21], off
	global_store_dwordx4 v[40:41], v[26:29], off offset:32
	global_store_dwordx4 v[40:41], v[2:5], off offset:64
	global_store_dwordx4 v[40:41], v[10:13], off offset:96
	s_and_saveexec_b64 s[52:53], vcc
	s_cbranch_execz .LBB0_474
	v_log_f32_e32 v0, v0
	v_lshlrev_b64 v[36:37], 5, v[34:35]
	v_lshl_add_u64 v[36:37], s[46:47], 0, v[36:37]
	v_add_f32_e32 v0, v138, v0
	global_store_dword v[36:37], v0, off
